# prepass Q/KK/decay stores non-temporal
# speedup vs baseline: 1.0040x; 1.0040x over previous
; __device__ __forceinline__ float bf2f(unsigned short u) { return __uint_as_float((unsigned)u << 16); }
; __device__ __forceinline__ unsigned short f2bf(float f) { return (unsigned short)(pk2(f, 0.f) & 0xffffu); }
; #define LBAR() do { asm volatile("s_waitcnt lgkmcnt(0)" ::: "memory"); __builtin_amdgcn_s_barrier(); asm volatile("" ::: "memory"); } while (0)
; __device__ __forceinline__ void hgrn_prepass(LAS unsigned char* lds, bf16* Q, bf16* KK, const float* LOGF, bf16* PBUF, float* DBUF, int bx, int G) {
;     ...
;         LBAR();
;         {
;             const float d0 = DEC[pk], d1 = DEC[128 + pk], d2 = DEC[256 + pk], d3 = DEC[384 + pk];
;             const float eq = pi == 0 ? 1.f : (pi == 1 ? d0 : (pi == 2 ? d0 * d1 : d0 * d1 * d2));
;             const float gk = pi == 3 ? 1.f : (pi == 2 ? d3 : (pi == 1 ? d2 * d3 : d1 * d2 * d3));
;             const size_t gb = (m0 + 16 * pi) * 1024 + hc + pk;
; #pragma unroll
;             for (int j = 0; j < 16; ++j) {
;                 const float qt = bf2f(Qt[(16 * pi + j) * 136 + pk]), k2 = bf2f(K2[(16 * pi + j) * 136 + pk]);
;                 Q[gb + (size_t)j * 1024] = f2bf(qt * eq); KK[gb + (size_t)j * 1024] = f2bf(k2 * gk);
;             }
.LBB0_1171:
	s_andn2_saveexec_b64 s[22:23], s[22:23]
	v_cmp_ne_u32_e32 vcc, 1, v14
	s_andn2_b64 s[2:3], s[20:21], exec
	s_and_b64 s[20:21], vcc, exec
	s_or_b64 s[20:21], s[2:3], s[20:21]
	s_mov_b64 s[2:3], exec
	s_or_b64 exec, exec, s[22:23]
	s_waitcnt lgkmcnt(0)
	v_mul_f32_e32 v11, v3, v4
	s_and_saveexec_b64 s[22:23], s[20:21]
	s_xor_b64 s[20:21], exec, s[22:23]
	v_mul_f32_e32 v100, v11, v5
	s_andn2_b64 s[2:3], s[2:3], exec
	s_or_b64 exec, exec, s[20:21]
	s_and_saveexec_b64 s[20:21], s[2:3]
	v_mul_f32_e32 v100, v4, v5
	s_or_b64 exec, exec, s[20:21]
	s_lshl_b32 s3, s24, 6
	ds_read_u16 v101, v51
	ds_read_u16 v102, v51 offset:34816
	s_ashr_i32 s2, s24, 8
	s_and_b32 s26, s3, 0x7c0
	s_ashr_i32 s3, s2, 31
	v_lshl_add_u64 v[12:13], s[26:27], 0, v[6:7]
	s_lshl_b32 s20, s24, 2
	s_lshl_b64 s[2:3], s[2:3], 21
	v_lshlrev_b64 v[12:13], 10, v[12:13]
	s_and_b32 s20, s20, 0x380
	v_lshl_add_u64 v[12:13], v[12:13], 0, s[2:3]
	v_or3_b32 v12, s20, v1, v12
	s_waitcnt lgkmcnt(1)
	v_lshlrev_b32_e32 v101, 16, v101
	v_mul_f32_e32 v101, v99, v101
	v_lshlrev_b64 v[12:13], 1, v[12:13]
	s_waitcnt lgkmcnt(0)
	v_lshlrev_b32_e32 v104, 16, v102
	v_cvt_pk_bf16_f32 v101, v101, s0
	v_lshl_add_u64 v[102:103], s[34:35], 0, v[12:13]
	v_readlane_b32 s2, v253, 0
	global_store_short v[102:103], v101, off nt
	v_mul_f32_e32 v101, v100, v104
	v_readlane_b32 s3, v253, 1
	v_cvt_pk_bf16_f32 v101, v101, s0
	s_nop 0
	v_lshl_add_u64 v[102:103], s[2:3], 0, v[12:13]
	global_store_short v[102:103], v101, off nt
	ds_read_u16 v101, v53
	ds_read_u16 v102, v53 offset:34816
	v_mov_b32_e32 v103, v13
	s_waitcnt lgkmcnt(1)
	v_lshlrev_b32_e32 v101, 16, v101
	s_waitcnt lgkmcnt(0)
	v_lshlrev_b32_e32 v106, 16, v102
	v_mul_f32_e32 v101, v99, v101
	v_or_b32_e32 v102, 0x800, v12
	v_cvt_pk_bf16_f32 v101, v101, s0
	v_lshl_add_u64 v[104:105], s[34:35], 0, v[102:103]
	global_store_short v[104:105], v101, off nt
	v_mul_f32_e32 v101, v100, v106
	v_cvt_pk_bf16_f32 v101, v101, s0
	v_lshl_add_u64 v[102:103], s[2:3], 0, v[102:103]
	global_store_short v[102:103], v101, off nt
	ds_read_u16 v101, v54
	ds_read_u16 v102, v54 offset:34816
	v_mov_b32_e32 v103, v13
	s_waitcnt lgkmcnt(1)
	v_lshlrev_b32_e32 v101, 16, v101
	s_waitcnt lgkmcnt(0)
	v_lshlrev_b32_e32 v106, 16, v102
	v_mul_f32_e32 v101, v99, v101
	v_or_b32_e32 v102, 0x1000, v12
	v_cvt_pk_bf16_f32 v101, v101, s0
	v_lshl_add_u64 v[104:105], s[34:35], 0, v[102:103]
	global_store_short v[104:105], v101, off nt
	v_mul_f32_e32 v101, v100, v106
	v_cvt_pk_bf16_f32 v101, v101, s0
	v_lshl_add_u64 v[102:103], s[2:3], 0, v[102:103]
	global_store_short v[102:103], v101, off nt
	ds_read_u16 v101, v55
	ds_read_u16 v102, v55 offset:34816
	v_mov_b32_e32 v103, v13
	s_waitcnt lgkmcnt(1)
	v_lshlrev_b32_e32 v101, 16, v101
	s_waitcnt lgkmcnt(0)
	v_lshlrev_b32_e32 v106, 16, v102
	v_mul_f32_e32 v101, v99, v101
	v_or_b32_e32 v102, 0x1800, v12
	v_cvt_pk_bf16_f32 v101, v101, s0
	v_lshl_add_u64 v[104:105], s[34:35], 0, v[102:103]
	global_store_short v[104:105], v101, off nt
	v_mul_f32_e32 v101, v100, v106
	v_cvt_pk_bf16_f32 v101, v101, s0
	v_lshl_add_u64 v[102:103], s[2:3], 0, v[102:103]
	global_store_short v[102:103], v101, off nt
	ds_read_u16 v101, v56
	ds_read_u16 v102, v56 offset:34816
	v_mov_b32_e32 v103, v13
	s_waitcnt lgkmcnt(1)
	v_lshlrev_b32_e32 v101, 16, v101
	s_waitcnt lgkmcnt(0)
	v_lshlrev_b32_e32 v106, 16, v102
	v_mul_f32_e32 v101, v99, v101
	v_or_b32_e32 v102, 0x2000, v12
	v_cvt_pk_bf16_f32 v101, v101, s0
	v_lshl_add_u64 v[104:105], s[34:35], 0, v[102:103]
	global_store_short v[104:105], v101, off nt
	v_mul_f32_e32 v101, v100, v106
	v_cvt_pk_bf16_f32 v101, v101, s0
	v_lshl_add_u64 v[102:103], s[2:3], 0, v[102:103]
	global_store_short v[102:103], v101, off nt
	ds_read_u16 v101, v57
	ds_read_u16 v102, v57 offset:34816
	v_mov_b32_e32 v103, v13
	s_waitcnt lgkmcnt(1)
	v_lshlrev_b32_e32 v101, 16, v101
	s_waitcnt lgkmcnt(0)
	v_lshlrev_b32_e32 v106, 16, v102
	v_mul_f32_e32 v101, v99, v101
	v_or_b32_e32 v102, 0x2800, v12
	v_cvt_pk_bf16_f32 v101, v101, s0
	v_lshl_add_u64 v[104:105], s[34:35], 0, v[102:103]
	global_store_short v[104:105], v101, off nt
	v_mul_f32_e32 v101, v100, v106
	v_cvt_pk_bf16_f32 v101, v101, s0
	v_lshl_add_u64 v[102:103], s[2:3], 0, v[102:103]
	global_store_short v[102:103], v101, off nt
	ds_read_u16 v101, v58
	ds_read_u16 v102, v58 offset:34816
	v_mov_b32_e32 v103, v13
	s_waitcnt lgkmcnt(1)
	v_lshlrev_b32_e32 v101, 16, v101
	s_waitcnt lgkmcnt(0)
	v_lshlrev_b32_e32 v106, 16, v102
	v_mul_f32_e32 v101, v99, v101
	v_or_b32_e32 v102, 0x3000, v12
	v_cvt_pk_bf16_f32 v101, v101, s0
	v_lshl_add_u64 v[104:105], s[34:35], 0, v[102:103]
	global_store_short v[104:105], v101, off nt
	v_mul_f32_e32 v101, v100, v106
	v_cvt_pk_bf16_f32 v101, v101, s0
	v_lshl_add_u64 v[102:103], s[2:3], 0, v[102:103]
	global_store_short v[102:103], v101, off nt
	ds_read_u16 v101, v59
	ds_read_u16 v102, v59 offset:34816
	v_mov_b32_e32 v103, v13
	s_waitcnt lgkmcnt(1)
	v_lshlrev_b32_e32 v101, 16, v101
	s_waitcnt lgkmcnt(0)
	v_lshlrev_b32_e32 v106, 16, v102
	v_mul_f32_e32 v101, v99, v101
	v_or_b32_e32 v102, 0x3800, v12
	v_cvt_pk_bf16_f32 v101, v101, s0
	v_lshl_add_u64 v[104:105], s[34:35], 0, v[102:103]
	global_store_short v[104:105], v101, off nt
	v_mul_f32_e32 v101, v100, v106
	v_cvt_pk_bf16_f32 v101, v101, s0
	v_lshl_add_u64 v[102:103], s[2:3], 0, v[102:103]
	global_store_short v[102:103], v101, off nt
	ds_read_u16 v101, v60
	ds_read_u16 v102, v60 offset:34816
	v_mov_b32_e32 v103, v13
	s_waitcnt lgkmcnt(1)
	v_lshlrev_b32_e32 v101, 16, v101
	s_waitcnt lgkmcnt(0)
; __device__ __forceinline__ float bf2f(unsigned short u) { return __uint_as_float((unsigned)u << 16); }
; __device__ __forceinline__ unsigned short f2bf(float f) { return (unsigned short)(pk2(f, 0.f) & 0xffffu); }
; __device__ __forceinline__ void hgrn_prepass(LAS unsigned char* lds, bf16* Q, bf16* KK, const float* LOGF, bf16* PBUF, float* DBUF, int bx, int G) {
;     ...
;             for (int j = 0; j < 16; ++j) {
;                 const float qt = bf2f(Qt[(16 * pi + j) * 136 + pk]), k2 = bf2f(K2[(16 * pi + j) * 136 + pk]);
;                 Q[gb + (size_t)j * 1024] = f2bf(qt * eq); KK[gb + (size_t)j * 1024] = f2bf(k2 * gk);
;             }
	v_lshlrev_b32_e32 v106, 16, v102
	v_mul_f32_e32 v101, v99, v101
	v_or_b32_e32 v102, 0x4000, v12
	v_cvt_pk_bf16_f32 v101, v101, s0
	v_lshl_add_u64 v[104:105], s[34:35], 0, v[102:103]
	global_store_short v[104:105], v101, off nt
	v_mul_f32_e32 v101, v100, v106
	v_cvt_pk_bf16_f32 v101, v101, s0
	v_lshl_add_u64 v[102:103], s[2:3], 0, v[102:103]
	global_store_short v[102:103], v101, off nt
	ds_read_u16 v101, v61
	ds_read_u16 v102, v61 offset:34816
	v_mov_b32_e32 v103, v13
	s_waitcnt lgkmcnt(1)
	v_lshlrev_b32_e32 v101, 16, v101
	s_waitcnt lgkmcnt(0)
	v_lshlrev_b32_e32 v106, 16, v102
	v_mul_f32_e32 v101, v99, v101
	v_or_b32_e32 v102, 0x4800, v12
	v_cvt_pk_bf16_f32 v101, v101, s0
	v_lshl_add_u64 v[104:105], s[34:35], 0, v[102:103]
	global_store_short v[104:105], v101, off nt
	v_mul_f32_e32 v101, v100, v106
	v_cvt_pk_bf16_f32 v101, v101, s0
	v_lshl_add_u64 v[102:103], s[2:3], 0, v[102:103]
	global_store_short v[102:103], v101, off nt
	ds_read_u16 v101, v62
	ds_read_u16 v102, v62 offset:34816
	v_mov_b32_e32 v103, v13
	s_waitcnt lgkmcnt(1)
	v_lshlrev_b32_e32 v101, 16, v101
	s_waitcnt lgkmcnt(0)
	v_lshlrev_b32_e32 v106, 16, v102
	v_mul_f32_e32 v101, v99, v101
	v_or_b32_e32 v102, 0x5000, v12
	v_cvt_pk_bf16_f32 v101, v101, s0
	v_lshl_add_u64 v[104:105], s[34:35], 0, v[102:103]
	global_store_short v[104:105], v101, off nt
	v_mul_f32_e32 v101, v100, v106
	v_cvt_pk_bf16_f32 v101, v101, s0
	v_lshl_add_u64 v[102:103], s[2:3], 0, v[102:103]
	global_store_short v[102:103], v101, off nt
	ds_read_u16 v101, v63
	ds_read_u16 v102, v63 offset:34816
	v_mov_b32_e32 v103, v13
	s_waitcnt lgkmcnt(1)
	v_lshlrev_b32_e32 v101, 16, v101
	s_waitcnt lgkmcnt(0)
	v_lshlrev_b32_e32 v106, 16, v102
	v_mul_f32_e32 v101, v99, v101
	v_or_b32_e32 v102, 0x5800, v12
	v_cvt_pk_bf16_f32 v101, v101, s0
	v_lshl_add_u64 v[104:105], s[34:35], 0, v[102:103]
	global_store_short v[104:105], v101, off nt
	v_mul_f32_e32 v101, v100, v106
	v_cvt_pk_bf16_f32 v101, v101, s0
	v_lshl_add_u64 v[102:103], s[2:3], 0, v[102:103]
	global_store_short v[102:103], v101, off nt
	ds_read_u16 v101, v64
	ds_read_u16 v102, v64 offset:34816
	v_mov_b32_e32 v103, v13
	s_waitcnt lgkmcnt(1)
	v_lshlrev_b32_e32 v101, 16, v101
	s_waitcnt lgkmcnt(0)
	v_lshlrev_b32_e32 v106, 16, v102
	v_mul_f32_e32 v101, v99, v101
	v_or_b32_e32 v102, 0x6000, v12
	v_cvt_pk_bf16_f32 v101, v101, s0
	v_lshl_add_u64 v[104:105], s[34:35], 0, v[102:103]
	global_store_short v[104:105], v101, off nt
	v_mul_f32_e32 v101, v100, v106
	v_cvt_pk_bf16_f32 v101, v101, s0
	v_lshl_add_u64 v[102:103], s[2:3], 0, v[102:103]
	global_store_short v[102:103], v101, off nt
	ds_read_u16 v101, v65
	ds_read_u16 v102, v65 offset:34816
	v_mov_b32_e32 v103, v13
	s_waitcnt lgkmcnt(1)
	v_lshlrev_b32_e32 v101, 16, v101
	s_waitcnt lgkmcnt(0)
	v_lshlrev_b32_e32 v106, 16, v102
	v_mul_f32_e32 v101, v99, v101
	v_or_b32_e32 v102, 0x6800, v12
	v_cvt_pk_bf16_f32 v101, v101, s0
	v_lshl_add_u64 v[104:105], s[34:35], 0, v[102:103]
	global_store_short v[104:105], v101, off nt
	v_mul_f32_e32 v101, v100, v106
	v_cvt_pk_bf16_f32 v101, v101, s0
	v_lshl_add_u64 v[102:103], s[2:3], 0, v[102:103]
	global_store_short v[102:103], v101, off nt
	ds_read_u16 v101, v66
	ds_read_u16 v102, v66 offset:34816
	v_mov_b32_e32 v103, v13
	s_waitcnt lgkmcnt(1)
	v_lshlrev_b32_e32 v101, 16, v101
	s_waitcnt lgkmcnt(0)
	v_lshlrev_b32_e32 v106, 16, v102
	v_mul_f32_e32 v101, v99, v101
	v_or_b32_e32 v102, 0x7000, v12
	v_cvt_pk_bf16_f32 v101, v101, s0
	v_lshl_add_u64 v[104:105], s[34:35], 0, v[102:103]
	global_store_short v[104:105], v101, off nt
	v_mul_f32_e32 v101, v100, v106
	v_cvt_pk_bf16_f32 v101, v101, s0
	v_lshl_add_u64 v[102:103], s[2:3], 0, v[102:103]
	global_store_short v[102:103], v101, off nt
	ds_read_u16 v101, v67
	ds_read_u16 v102, v67 offset:34816
	v_or_b32_e32 v12, 0x7800, v12
	s_waitcnt lgkmcnt(1)
; __device__ __forceinline__ float bf2f(unsigned short u) { return __uint_as_float((unsigned)u << 16); }
; __device__ __forceinline__ unsigned short f2bf(float f) { return (unsigned short)(pk2(f, 0.f) & 0xffffu); }
; __device__ __forceinline__ void hgrn_prepass(LAS unsigned char* lds, bf16* Q, bf16* KK, const float* LOGF, bf16* PBUF, float* DBUF, int bx, int G) {
;     ...
;             for (int j = 0; j < 16; ++j) {
;                 const float qt = bf2f(Qt[(16 * pi + j) * 136 + pk]), k2 = bf2f(K2[(16 * pi + j) * 136 + pk]);
;                 Q[gb + (size_t)j * 1024] = f2bf(qt * eq); KK[gb + (size_t)j * 1024] = f2bf(k2 * gk);
;             }
; #pragma unroll
;             for (int jj = 0; jj < 12; ++jj) {
;                 const int r = 12 * pi + jj, tile = r >> 4, rr = r & 15;
;                 const float f = tile == 0 ? d1 : (tile == 1 ? d2 : d1 * d2);
;                 QX[r * 136 + pk] = f2bf(bf2f(Qt[((tile == 0 ? 32 : 48) + rr) * 136 + pk]) * f);
;             }
;             if (pi == 0) DBUF[(size_t)u * 128 + pk] = (d0 * d1) * (d2 * d3);
	v_lshlrev_b32_e32 v101, 16, v101
	v_mul_f32_e32 v99, v99, v101
	s_waitcnt lgkmcnt(0)
	v_lshlrev_b32_e32 v104, 16, v102
	v_cvt_pk_bf16_f32 v99, v99, s0
	v_lshl_add_u64 v[102:103], s[34:35], 0, v[12:13]
	global_store_short v[102:103], v99, off nt
	v_mul_f32_e32 v99, v100, v104
	v_cvt_pk_bf16_f32 v99, v99, s0
	v_lshl_add_u64 v[12:13], s[2:3], 0, v[12:13]
	global_store_short v[12:13], v99, off nt
	ds_read_u16 v13, v75
	v_cndmask_b32_e64 v12, v11, v4, s[6:7]
	v_cndmask_b32_e64 v12, v12, v3, s[8:9]
	s_waitcnt lgkmcnt(0)
	v_lshlrev_b32_e32 v13, 16, v13
	v_mul_f32_e32 v13, v12, v13
	v_cvt_pk_bf16_f32 v13, v13, s0
	ds_write_b16 v76, v13 offset:52224
	ds_read_u16 v13, v77
	s_waitcnt lgkmcnt(0)
	v_lshlrev_b32_e32 v13, 16, v13
	v_mul_f32_e32 v13, v12, v13
	v_cvt_pk_bf16_f32 v13, v13, s0
	ds_write_b16 v78, v13 offset:52224
	ds_read_u16 v13, v79
	s_waitcnt lgkmcnt(0)
	v_lshlrev_b32_e32 v13, 16, v13
	v_mul_f32_e32 v13, v12, v13
	v_cvt_pk_bf16_f32 v13, v13, s0
	ds_write_b16 v78, v13 offset:52496
	ds_read_u16 v13, v80
	s_waitcnt lgkmcnt(0)
	v_lshlrev_b32_e32 v13, 16, v13
	v_mul_f32_e32 v12, v12, v13
	v_cvt_pk_bf16_f32 v12, v12, s0
	ds_write_b16 v78, v12 offset:52768
	ds_read_u16 v13, v81
	v_cndmask_b32_e64 v12, v11, v4, s[10:11]
	v_cndmask_b32_e64 v12, v12, v3, s[12:13]
	s_waitcnt lgkmcnt(0)
	v_lshlrev_b32_e32 v13, 16, v13
	v_mul_f32_e32 v12, v12, v13
	v_cvt_pk_bf16_f32 v12, v12, s0
	ds_write_b16 v78, v12 offset:53040
	ds_read_u16 v13, v82
	v_cndmask_b32_e64 v12, v11, v4, s[14:15]
	v_cndmask_b32_e64 v12, v12, v3, s[36:37]
	s_waitcnt lgkmcnt(0)
	v_lshlrev_b32_e32 v13, 16, v13
	v_mul_f32_e32 v12, v12, v13
	v_cvt_pk_bf16_f32 v12, v12, s0
	ds_write_b16 v78, v12 offset:53312
	ds_read_u16 v13, v83
	v_cndmask_b32_e64 v12, v11, v4, s[40:41]
	v_cndmask_b32_e64 v12, v12, v3, s[42:43]
	s_waitcnt lgkmcnt(0)
	v_lshlrev_b32_e32 v13, 16, v13
	v_mul_f32_e32 v12, v12, v13
	v_cvt_pk_bf16_f32 v12, v12, s0
	ds_write_b16 v78, v12 offset:53584
	ds_read_u16 v13, v84
	v_cndmask_b32_e64 v12, v11, v4, s[44:45]
	v_cndmask_b32_e64 v12, v12, v3, s[46:47]
	s_waitcnt lgkmcnt(0)
	v_lshlrev_b32_e32 v13, 16, v13
	v_mul_f32_e32 v12, v12, v13
	v_cvt_pk_bf16_f32 v12, v12, s0
	ds_write_b16 v78, v12 offset:53856
	ds_read_u16 v13, v85
	v_cndmask_b32_e64 v12, v11, v4, s[48:49]
	v_cndmask_b32_e64 v12, v12, v3, s[50:51]
	s_waitcnt lgkmcnt(0)
	v_lshlrev_b32_e32 v13, 16, v13
	v_mul_f32_e32 v12, v12, v13
	v_cvt_pk_bf16_f32 v12, v12, s0
	ds_write_b16 v78, v12 offset:54128
	ds_read_u16 v13, v86
	v_cndmask_b32_e64 v12, v11, v4, s[52:53]
	v_cndmask_b32_e64 v12, v12, v3, s[54:55]
	s_waitcnt lgkmcnt(0)
	v_lshlrev_b32_e32 v13, 16, v13
	v_mul_f32_e32 v12, v12, v13
	v_cvt_pk_bf16_f32 v12, v12, s0
	ds_write_b16 v78, v12 offset:54400
	ds_read_u16 v13, v87
	v_cndmask_b32_e64 v12, v11, v4, s[56:57]
	v_cndmask_b32_e64 v12, v12, v3, s[58:59]
	v_cndmask_b32_e64 v11, v11, v4, s[60:61]
	v_cndmask_b32_e64 v11, v11, v3, s[62:63]
	s_waitcnt lgkmcnt(0)
	v_lshlrev_b32_e32 v13, 16, v13
	v_mul_f32_e32 v12, v12, v13
	v_cvt_pk_bf16_f32 v12, v12, s0
	ds_write_b16 v78, v12 offset:54672
	ds_read_u16 v12, v88
	s_waitcnt lgkmcnt(0)
	v_lshlrev_b32_e32 v12, 16, v12
	v_mul_f32_e32 v11, v11, v12
	v_cvt_pk_bf16_f32 v11, v11, s0
	ds_write_b16 v78, v11 offset:54944
	s_and_saveexec_b64 s[2:3], s[0:1]
	s_cbranch_execz .LBB0_1179
	v_mov_b32_e32 v12, v2
	v_mov_b32_e32 v13, v4
	v_mov_b32_e32 v4, v3
	s_ashr_i32 s25, s24, 31
	v_pk_mul_f32 v[2:3], v[12:13], v[4:5]
	s_lshl_b64 s[20:21], s[24:25], 9
	v_mul_f32_e32 v4, v2, v3
	v_lshl_add_u64 v[2:3], v[8:9], 0, s[20:21]
	global_store_dword v[2:3], v4, off
